# stack7 plus producer running-address fetch and the redundant s_nop 7 behind the scan y MFMA trimmed (wait states now supplied by the moved state-update MFMAs)
# speedup vs baseline: 1.0064x; 1.0005x over previous
; __device__ __forceinline__ void ck_consume(const LAS unsigned char* slot, f32x4 (&sacc)[4], LAS unsigned char* st  , int lane, int cw, f32x4& yout, u32x2& vout, f32x4& dout) {
;     const int n = lane & 15, g = lane >> 4;
;     const f32x4 zero4 = {0.f, 0.f, 0.f, 0.f};
;     u32x2 qlo[2][2], qhi[2][2], mn[4], blo[4], bhi[4]; f32x4 gm[4];
; #pragma unroll
;     for (int ks = 0; ks < 2; ++ks)
; #pragma unroll
;         for (int mt = 0; mt < 2; ++mt) { const LAS unsigned char* p = slot + CK_QR + (16 * mt + n) * 136 + (32 * ks + 4 * g) * 2; qlo[ks][mt] = ck_ld8(p); qhi[ks][mt] = ck_ld8(p + 32); }
;     const u32x2 vq = ck_ld8(slot + CK_VT + (16 * cw + n) * 40 + 8 * g);
;     const u32x2 mk = ck_ld8(slot + CK_MK + n * 40 + 8 * g);
; #pragma unroll
;     for (int j = 0; j < 4; ++j) mn[j] = ck_ld8(slot + CK_MN + j * 640 + n * 40 + 8 * g);
;     const u32x2 ylo = ck_ld8(slot + CK_MY + n * 72 + 8 * g), yhi = ck_ld8(slot + CK_MY + n * 72 + 8 * g + 32);
; #pragma unroll
;     for (int kb = 0; kb < 4; ++kb) { const LAS unsigned char* p = slot + CK_BK + (16 * kb + n) * 72 + 8 * g; blo[kb] = ck_ld8(p); bhi[kb] = ck_ld8(p + 32); gm[kb] = *(const LAS f32x4*)(slot + CK_GM + (16 * kb + 4 * g) * 4); }
;     f32x4 xacc[2] = {zero4, zero4};
; #pragma unroll
;     for (int ks = 0; ks < 2; ++ks) {
;         const pg8::bf16x8 Bs = ck_frag(pkc(sacc[2 * ks][0], sacc[2 * ks][1]), pkc(sacc[2 * ks][2], sacc[2 * ks][3]), pkc(sacc[2 * ks + 1][0], sacc[2 * ks + 1][1]), pkc(sacc[2 * ks + 1][2], sacc[2 * ks + 1][3]));
; #pragma unroll
;         for (int mt = 0; mt < 2; ++mt) xacc[mt] = __builtin_amdgcn_mfma_f32_16x16x32_bf16(ck_frag(qlo[ks][mt].x, qlo[ks][mt].y, qhi[ks][mt].x, qhi[ks][mt].y), Bs, xacc[mt], 0, 0, 0);
;     }
;     f32x4 Z = __builtin_amdgcn_mfma_f32_16x16x32_bf16(ck_frag(0u, 0u, mk.x, mk.y), ck_frag(0u, 0u, vq.x, vq.y), xacc[0], 0, 0, 0);
; #pragma unroll
;     for (int j = 0; j < 4; ++j) Z = __builtin_amdgcn_mfma_f32_16x16x32_bf16(ck_frag(mn[j].x, mn[j].y, 0u, 0u), ck_frag(pkc(Z[0], Z[1]), pkc(Z[2], Z[3]), vq.x, vq.y), Z, 0, 0, 0);
;     const pg8::bf16x8 UV = ck_frag(pkc(Z[0], Z[1]), pkc(Z[2], Z[3]), vq.x, vq.y);
;     { const f32x4 y = __builtin_amdgcn_mfma_f32_16x16x32_bf16(ck_frag(ylo.x, ylo.y, yhi.x, yhi.y), UV, xacc[1], 0, 0, 0);
;       yout = y; vout = vq; dout = *(const LAS f32x4*)(slot + CK_DOT + 16 * g);
; #pragma unroll
.LBB0_118:
	s_andn2_b64 vcc, exec, s[34:35]
	s_cbranch_vccnz .LBB0_115
	s_and_b32 s2, s29, 4
	s_lshl_b32 s7, s2, 14
	s_add_i32 s7, s7, 0
	v_add_u32_e32 v32, s7, v166
	v_add_u32_e32 v33, v32, v167
	ds_read2_b64 v[36:39], v33 offset1:4
	v_add_u32_e32 v34, 0x800, v33
	s_waitcnt vmcnt(3)
	v_add_u32_e32 v44, v32, v169
	ds_read2_b64 v[40:43], v34 offset0:16 offset1:20
	ds_read2_b64 v[64:67], v33 offset0:8 offset1:12
	ds_read2_b64 v[68:71], v34 offset0:24 offset1:28
	v_add_u32_e32 v34, 0x2800, v44
	ds_read2_b64 v[72:75], v34 offset0:160 offset1:240
	s_waitcnt vmcnt(1)
	v_cvt_pk_bf16_f32 v104, v92, v93
	s_waitcnt vmcnt(0)
	v_cvt_pk_bf16_f32 v105, v94, v95
	v_cvt_pk_bf16_f32 v106, v88, v89
	v_cvt_pk_bf16_f32 v107, v90, v91
	v_add_u32_e32 v33, v32, v168
	v_add_u32_e32 v34, 0x3000, v44
	s_waitcnt lgkmcnt(4)
	v_mfma_f32_16x16x32_bf16 v[36:39], v[36:39], v[104:107], 0
	ds_read2_b64 v[76:79], v34 offset0:64 offset1:144
	ds_read_b64 v[34:35], v33 offset:8960
	ds_read_b64 v[96:97], v44 offset:14080
	v_add3_u32 v33, s7, v170, v166
	v_add_u32_e32 v33, 0x3800, v33
	s_waitcnt lgkmcnt(6)
	v_mfma_f32_16x16x32_bf16 v[40:43], v[40:43], v[104:107], 0
	v_cvt_pk_bf16_f32 v104, v84, v85
	v_cvt_pk_bf16_f32 v105, v86, v87
	v_cvt_pk_bf16_f32 v106, v80, v81
	v_cvt_pk_bf16_f32 v107, v82, v83
	ds_read2_b64 v[100:103], v33 offset0:48 offset1:52
	v_add_u32_e32 v33, v32, v170
	s_waitcnt lgkmcnt(6)
	v_mfma_f32_16x16x32_bf16 v[36:39], v[64:67], v[104:107], v[36:39]
	v_mov_b32_e32 v64, v129
	v_mov_b32_e32 v65, v129
	s_waitcnt lgkmcnt(4)
	v_mov_b32_e32 v66, v72
	v_mov_b32_e32 v67, v73
	v_add_u32_e32 v108, s7, v171
	v_add_u32_e32 v44, 0x1000, v33
	v_add_u32_e32 v33, 0x1800, v33
	ds_read2_b64 v[56:59], v44 offset0:32 offset1:36
	ds_read2_b64 v[52:55], v44 offset0:176 offset1:180
	ds_read_b128 v[48:51], v108 offset:15872
	ds_read_b128 v[44:47], v108 offset:15936
	ds_read2_b64 v[60:63], v33 offset0:64 offset1:68
	v_add_u32_e32 v72, v32, v172
	v_mov_b32_e32 v32, v129
	v_mov_b32_e32 v33, v129
	v_mfma_f32_16x16x32_bf16 v[40:43], v[68:71], v[104:107], v[40:43]
	s_waitcnt lgkmcnt(8)
	v_mov_b32_e32 v68, v76
	v_mov_b32_e32 v69, v77
	v_mov_b32_e32 v70, v129
	s_waitcnt lgkmcnt(7)
	v_mfma_f32_16x16x32_bf16 v[36:39], v[64:67], v[32:35], v[36:39]
	v_mov_b32_e32 v64, v74
	v_mov_b32_e32 v65, v75
	v_mov_b32_e32 v66, v129
	v_mov_b32_e32 v67, v129
	v_mov_b32_e32 v71, v129
	s_nop 2
	v_cvt_pk_bf16_f32 v32, v36, v37
	v_cvt_pk_bf16_f32 v33, v38, v39
	v_mov_b32_e32 v98, v129
	v_mov_b32_e32 v99, v129
	v_mfma_f32_16x16x32_bf16 v[36:39], v[64:67], v[32:35], v[36:39]
	v_mov_b32_e32 v64, v78
	v_mov_b32_e32 v65, v79
	v_add_u32_e32 v72, 0x1000, v72
	s_lshl_b32 s33, s2, 9
	s_add_i32 s33, s33, 0
	s_nop 2
	v_cvt_pk_bf16_f32 v32, v36, v37
	v_cvt_pk_bf16_f32 v33, v38, v39
	s_add_i32 s33, s33, 0x24800
	s_nop 0
	v_mfma_f32_16x16x32_bf16 v[36:39], v[68:71], v[32:35], v[36:39]
	s_nop 7
	v_cvt_pk_bf16_f32 v32, v36, v37
	v_cvt_pk_bf16_f32 v33, v38, v39
	s_nop 1
	v_mfma_f32_16x16x32_bf16 v[36:39], v[64:67], v[32:35], v[36:39]
	ds_read2_b64 v[64:67], v72 offset0:32 offset1:36
	ds_read_b128 v[76:79], v108 offset:16000
	ds_read_b128 v[72:75], v108 offset:16064
	s_nop 4
	v_cvt_pk_bf16_f32 v32, v36, v37
	v_cvt_pk_bf16_f32 v33, v38, v39
	s_waitcnt lgkmcnt(9)
	s_nop 0
	v_mfma_f32_16x16x32_bf16 v[36:39], v[96:99], v[32:35], v[36:39]
	v_add_u32_e32 v96, s33, v173
	s_nop 6
	v_cvt_pk_bf16_f32 v32, v36, v37
	v_cvt_pk_bf16_f32 v33, v38, v39
	ds_read_b128 v[36:39], v108 offset:16128
	s_waitcnt lgkmcnt(9)
	v_mfma_f32_16x16x32_bf16 v[40:43], v[100:103], v[32:35], v[40:43]
	s_waitcnt lgkmcnt(4)
	v_mfma_f32_16x16x32_bf16 v[56:59], v[56:59], v[32:35], v[92:95]
	s_waitcnt lgkmcnt(3)
	v_mfma_f32_16x16x32_bf16 v[52:55], v[52:55], v[32:35], v[88:91]
	s_waitcnt lgkmcnt(0)
	v_mfma_f32_16x16x32_bf16 v[60:63], v[60:63], v[32:35], v[84:87]
	s_waitcnt lgkmcnt(0)
	v_mfma_f32_16x16x32_bf16 v[80:83], v[64:67], v[32:35], v[80:83]
	s_nop 0
	v_mul_f32_e32 v71, v40, v40
	v_mov_b32_dpp v68, v40 quad_perm:[1,0,3,2] row_mask:0xf bank_mask:0xf bound_ctrl:1
	v_mov_b32_e32 v70, v40
	v_mov_b32_dpp v69, v71 quad_perm:[1,0,3,2] row_mask:0xf bank_mask:0xf bound_ctrl:1
	v_pk_add_f32 v[68:69], v[70:71], v[68:69]
	s_nop 1
	v_mov_b32_dpp v70, v68 quad_perm:[2,3,0,1] row_mask:0xf bank_mask:0xf bound_ctrl:1
	v_mov_b32_dpp v71, v69 quad_perm:[2,3,0,1] row_mask:0xf bank_mask:0xf bound_ctrl:1
	v_pk_add_f32 v[68:69], v[68:69], v[70:71]
	s_nop 1
	v_mov_b32_dpp v70, v68 row_half_mirror row_mask:0xf bank_mask:0xf bound_ctrl:1
	v_mov_b32_dpp v71, v69 row_half_mirror row_mask:0xf bank_mask:0xf bound_ctrl:1
	v_pk_add_f32 v[68:69], v[68:69], v[70:71]
	s_nop 1
	v_mov_b32_dpp v70, v68 row_mirror row_mask:0xf bank_mask:0xf bound_ctrl:1
	v_mov_b32_dpp v71, v69 row_mirror row_mask:0xf bank_mask:0xf bound_ctrl:1
	s_and_saveexec_b64 s[34:35], s[40:41]
	v_pk_add_f32 v[68:69], v[68:69], v[70:71]
	ds_write_b64 v96, v[68:69]
	s_or_b64 exec, exec, s[34:35]
	v_mul_f32_e32 v71, v41, v41
	v_mov_b32_dpp v68, v41 quad_perm:[1,0,3,2] row_mask:0xf bank_mask:0xf bound_ctrl:1
	v_mov_b32_e32 v70, v41
	v_mov_b32_dpp v69, v71 quad_perm:[1,0,3,2] row_mask:0xf bank_mask:0xf bound_ctrl:1
	v_pk_add_f32 v[68:69], v[70:71], v[68:69]
	s_nop 1
	v_mov_b32_dpp v70, v68 quad_perm:[2,3,0,1] row_mask:0xf bank_mask:0xf bound_ctrl:1
	v_mov_b32_dpp v71, v69 quad_perm:[2,3,0,1] row_mask:0xf bank_mask:0xf bound_ctrl:1
	v_pk_add_f32 v[68:69], v[68:69], v[70:71]
	s_nop 1
	v_mov_b32_dpp v70, v68 row_half_mirror row_mask:0xf bank_mask:0xf bound_ctrl:1
	v_mov_b32_dpp v71, v69 row_half_mirror row_mask:0xf bank_mask:0xf bound_ctrl:1
	v_pk_add_f32 v[68:69], v[68:69], v[70:71]
	s_nop 1
	v_mov_b32_dpp v70, v68 row_mirror row_mask:0xf bank_mask:0xf bound_ctrl:1
; __device__ __forceinline__ void ck_consume(const LAS unsigned char* slot, f32x4 (&sacc)[4], LAS unsigned char* st  , int lane, int cw, f32x4& yout, u32x2& vout, f32x4& dout) {
;     const int n = lane & 15, g = lane >> 4;
;     const f32x4 zero4 = {0.f, 0.f, 0.f, 0.f};
;     u32x2 qlo[2][2], qhi[2][2], mn[4], blo[4], bhi[4]; f32x4 gm[4];
; #pragma unroll
;     for (int ks = 0; ks < 2; ++ks)
; #pragma unroll
;         for (int mt = 0; mt < 2; ++mt) { const LAS unsigned char* p = slot + CK_QR + (16 * mt + n) * 136 + (32 * ks + 4 * g) * 2; qlo[ks][mt] = ck_ld8(p); qhi[ks][mt] = ck_ld8(p + 32); }
;     const u32x2 vq = ck_ld8(slot + CK_VT + (16 * cw + n) * 40 + 8 * g);
;     const u32x2 mk = ck_ld8(slot + CK_MK + n * 40 + 8 * g);
; #pragma unroll
;     for (int j = 0; j < 4; ++j) mn[j] = ck_ld8(slot + CK_MN + j * 640 + n * 40 + 8 * g);
;     const u32x2 ylo = ck_ld8(slot + CK_MY + n * 72 + 8 * g), yhi = ck_ld8(slot + CK_MY + n * 72 + 8 * g + 32);
; #pragma unroll
;     for (int kb = 0; kb < 4; ++kb) { const LAS unsigned char* p = slot + CK_BK + (16 * kb + n) * 72 + 8 * g; blo[kb] = ck_ld8(p); bhi[kb] = ck_ld8(p + 32); gm[kb] = *(const LAS f32x4*)(slot + CK_GM + (16 * kb + 4 * g) * 4); }
;     f32x4 xacc[2] = {zero4, zero4};
; #pragma unroll
;     for (int ks = 0; ks < 2; ++ks) {
;         const pg8::bf16x8 Bs = ck_frag(pkc(sacc[2 * ks][0], sacc[2 * ks][1]), pkc(sacc[2 * ks][2], sacc[2 * ks][3]), pkc(sacc[2 * ks + 1][0], sacc[2 * ks + 1][1]), pkc(sacc[2 * ks + 1][2], sacc[2 * ks + 1][3]));
; #pragma unroll
;         for (int mt = 0; mt < 2; ++mt) xacc[mt] = __builtin_amdgcn_mfma_f32_16x16x32_bf16(ck_frag(qlo[ks][mt].x, qlo[ks][mt].y, qhi[ks][mt].x, qhi[ks][mt].y), Bs, xacc[mt], 0, 0, 0);
;     }
;     f32x4 Z = __builtin_amdgcn_mfma_f32_16x16x32_bf16(ck_frag(0u, 0u, mk.x, mk.y), ck_frag(0u, 0u, vq.x, vq.y), xacc[0], 0, 0, 0);
; #pragma unroll
;     for (int j = 0; j < 4; ++j) Z = __builtin_amdgcn_mfma_f32_16x16x32_bf16(ck_frag(mn[j].x, mn[j].y, 0u, 0u), ck_frag(pkc(Z[0], Z[1]), pkc(Z[2], Z[3]), vq.x, vq.y), Z, 0, 0, 0);
;     const pg8::bf16x8 UV = ck_frag(pkc(Z[0], Z[1]), pkc(Z[2], Z[3]), vq.x, vq.y);
;     { const f32x4 y = __builtin_amdgcn_mfma_f32_16x16x32_bf16(ck_frag(ylo.x, ylo.y, yhi.x, yhi.y), UV, xacc[1], 0, 0, 0);
;       yout = y; vout = vq; dout = *(const LAS f32x4*)(slot + CK_DOT + 16 * g);
; #pragma unroll
	v_mov_b32_dpp v71, v69 row_mirror row_mask:0xf bank_mask:0xf bound_ctrl:1
	s_and_saveexec_b64 s[34:35], s[40:41]
	v_pk_add_f32 v[68:69], v[68:69], v[70:71]
	ds_write_b64 v96, v[68:69] offset:32
	s_or_b64 exec, exec, s[34:35]
	v_mul_f32_e32 v71, v42, v42
	v_mov_b32_dpp v68, v42 quad_perm:[1,0,3,2] row_mask:0xf bank_mask:0xf bound_ctrl:1
	v_mov_b32_e32 v70, v42
	v_mov_b32_dpp v69, v71 quad_perm:[1,0,3,2] row_mask:0xf bank_mask:0xf bound_ctrl:1
	v_pk_add_f32 v[68:69], v[70:71], v[68:69]
	s_nop 1
	v_mov_b32_dpp v70, v68 quad_perm:[2,3,0,1] row_mask:0xf bank_mask:0xf bound_ctrl:1
	v_mov_b32_dpp v71, v69 quad_perm:[2,3,0,1] row_mask:0xf bank_mask:0xf bound_ctrl:1
	v_pk_add_f32 v[68:69], v[68:69], v[70:71]
	s_nop 1
	v_mov_b32_dpp v70, v68 row_half_mirror row_mask:0xf bank_mask:0xf bound_ctrl:1
	v_mov_b32_dpp v71, v69 row_half_mirror row_mask:0xf bank_mask:0xf bound_ctrl:1
	v_pk_add_f32 v[68:69], v[68:69], v[70:71]
	s_nop 1
	v_mov_b32_dpp v70, v68 row_mirror row_mask:0xf bank_mask:0xf bound_ctrl:1
	v_mov_b32_dpp v71, v69 row_mirror row_mask:0xf bank_mask:0xf bound_ctrl:1
	s_and_saveexec_b64 s[34:35], s[40:41]
	v_pk_add_f32 v[68:69], v[68:69], v[70:71]
	ds_write_b64 v96, v[68:69] offset:64
	s_or_b64 exec, exec, s[34:35]
	v_mul_f32_e32 v71, v43, v43
	v_mov_b32_dpp v68, v43 quad_perm:[1,0,3,2] row_mask:0xf bank_mask:0xf bound_ctrl:1
	v_mov_b32_e32 v70, v43
	v_mov_b32_dpp v69, v71 quad_perm:[1,0,3,2] row_mask:0xf bank_mask:0xf bound_ctrl:1
	v_pk_add_f32 v[68:69], v[70:71], v[68:69]
	s_nop 1
	v_mov_b32_dpp v70, v68 quad_perm:[2,3,0,1] row_mask:0xf bank_mask:0xf bound_ctrl:1
	v_mov_b32_dpp v71, v69 quad_perm:[2,3,0,1] row_mask:0xf bank_mask:0xf bound_ctrl:1
	v_pk_add_f32 v[68:69], v[68:69], v[70:71]
	s_nop 1
	v_mov_b32_dpp v70, v68 row_half_mirror row_mask:0xf bank_mask:0xf bound_ctrl:1
	v_mov_b32_dpp v71, v69 row_half_mirror row_mask:0xf bank_mask:0xf bound_ctrl:1
	v_pk_add_f32 v[68:69], v[68:69], v[70:71]
	s_nop 1
	v_mov_b32_dpp v70, v68 row_mirror row_mask:0xf bank_mask:0xf bound_ctrl:1
	v_mov_b32_dpp v71, v69 row_mirror row_mask:0xf bank_mask:0xf bound_ctrl:1
	s_and_saveexec_b64 s[34:35], s[40:41]
	v_pk_add_f32 v[68:69], v[68:69], v[70:71]
	ds_write_b64 v96, v[68:69] offset:96
	s_or_b64 exec, exec, s[34:35]
	v_ashrrev_i32_e32 v71, 31, v128
	v_mov_b32_e32 v70, v128
	v_lshl_add_u64 v[158:159], v[70:71], 1, v[156:157]
	s_movk_i32 s7, 0x2000
	v_add_co_u32_e32 v70, vcc, s7, v158
	s_movk_i32 s7, 0x3000
	s_nop 0
	v_addc_co_u32_e32 v71, vcc, 0, v159, vcc
	v_lshl_add_u64 v[68:69], v[128:129], 1, v[156:157]
	global_load_ushort v232, v[70:71], off offset:-4096
	global_load_ushort v233, v[70:71], off
	v_mov_b32_e32 v110, v129
	s_waitcnt lgkmcnt(6)
	s_nop 0
	v_pk_mul_f32 v[70:71], v[50:51], v[58:59]
	v_mov_b32_e32 v111, v129
	v_cvt_pk_bf16_f32 v117, v70, v71
	v_add_co_u32_e32 v32, vcc, s7, v158
	s_or_b32 s7, s2, 1
	s_nop 0
	v_addc_co_u32_e32 v33, vcc, 0, v159, vcc
	global_load_ushort v234, v[68:69], off
	global_load_ushort v235, v[32:33], off
	s_lshl_b32 s33, s7, 14
	s_add_i32 s33, s33, 0
	v_add_u32_e32 v32, s33, v166
	v_add_u32_e32 v33, v32, v167
	v_pk_mul_f32 v[68:69], v[48:49], v[56:57]
	ds_read2_b64 v[48:51], v33 offset1:4
	v_pk_mul_f32 v[64:65], v[44:45], v[52:53]
	v_add_u32_e32 v44, 0x800, v33
	v_pk_mul_f32 v[66:67], v[46:47], v[54:55]
	ds_read2_b64 v[52:55], v44 offset0:16 offset1:20
	ds_read2_b64 v[92:95], v33 offset0:8 offset1:12
	ds_read2_b64 v[96:99], v44 offset0:24 offset1:28
	v_add_u32_e32 v44, v32, v169
	v_add_u32_e32 v45, 0x2800, v44
	ds_read2_b64 v[100:103], v45 offset0:160 offset1:240
	v_cvt_pk_bf16_f32 v116, v68, v69
	v_cvt_pk_bf16_f32 v118, v64, v65
	v_cvt_pk_bf16_f32 v119, v66, v67
	s_waitcnt lgkmcnt(7)
	v_pk_mul_f32 v[62:63], v[78:79], v[62:63]
	v_pk_mul_f32 v[60:61], v[76:77], v[60:61]
	s_waitcnt lgkmcnt(4)
	v_mfma_f32_16x16x32_bf16 v[48:51], v[48:51], v[116:119], 0
	v_mul_f32_e64 v58, v74, v82
	v_mul_f32_e64 v59, v75, v83
	v_pk_mul_f32 v[56:57], v[72:73], v[80:81]
	v_add_u32_e32 v33, v32, v168
	s_waitcnt lgkmcnt(3)
	v_mfma_f32_16x16x32_bf16 v[52:55], v[52:55], v[116:119], 0
	v_cvt_pk_bf16_f32 v116, v60, v61
	v_cvt_pk_bf16_f32 v117, v62, v63
	v_cvt_pk_bf16_f32 v118, v56, v57
	v_cvt_pk_bf16_f32 v119, v58, v59
	v_add_u32_e32 v45, 0x3000, v44
	ds_read2_b64 v[104:107], v45 offset0:64 offset1:144
	ds_read_b64 v[46:47], v33 offset:8960
	ds_read_b64 v[108:109], v44 offset:14080
	s_waitcnt lgkmcnt(5)
	v_mfma_f32_16x16x32_bf16 v[48:51], v[92:95], v[116:119], v[48:51]
	v_mov_b32_e32 v92, v129
	v_mov_b32_e32 v93, v129
	s_waitcnt lgkmcnt(3)
	v_mov_b32_e32 v94, v100
	v_mov_b32_e32 v95, v101
	v_add3_u32 v33, s33, v170, v166
	v_add_u32_e32 v33, 0x3800, v33
	v_add_u32_e32 v44, v32, v170
	ds_read2_b64 v[112:115], v33 offset0:48 offset1:52
	v_add_u32_e32 v33, s33, v171
	v_add_u32_e32 v45, 0x1000, v44
	v_add_u32_e32 v44, 0x1800, v44
	ds_read2_b64 v[88:91], v45 offset0:32 offset1:36
	ds_read2_b64 v[80:83], v45 offset0:176 offset1:180
	ds_read_b128 v[76:79], v33 offset:15872
	ds_read_b128 v[72:75], v33 offset:15936
	ds_read2_b64 v[84:87], v44 offset0:64 offset1:68
	v_mov_b32_e32 v44, v129
	v_mov_b32_e32 v45, v129
	v_mfma_f32_16x16x32_bf16 v[52:55], v[96:99], v[116:119], v[52:55]
	s_waitcnt lgkmcnt(8)
	v_mov_b32_e32 v96, v104
	v_mov_b32_e32 v97, v105
	v_mov_b32_e32 v98, v129
	s_waitcnt lgkmcnt(7)
; __device__ __forceinline__ void ck_consume(const LAS unsigned char* slot, f32x4 (&sacc)[4], LAS unsigned char* st  , int lane, int cw, f32x4& yout, u32x2& vout, f32x4& dout) {
;     const int n = lane & 15, g = lane >> 4;
;     const f32x4 zero4 = {0.f, 0.f, 0.f, 0.f};
;     u32x2 qlo[2][2], qhi[2][2], mn[4], blo[4], bhi[4]; f32x4 gm[4];
; #pragma unroll
;     for (int ks = 0; ks < 2; ++ks)
; #pragma unroll
;         for (int mt = 0; mt < 2; ++mt) { const LAS unsigned char* p = slot + CK_QR + (16 * mt + n) * 136 + (32 * ks + 4 * g) * 2; qlo[ks][mt] = ck_ld8(p); qhi[ks][mt] = ck_ld8(p + 32); }
;     const u32x2 vq = ck_ld8(slot + CK_VT + (16 * cw + n) * 40 + 8 * g);
;     const u32x2 mk = ck_ld8(slot + CK_MK + n * 40 + 8 * g);
; #pragma unroll
;     for (int j = 0; j < 4; ++j) mn[j] = ck_ld8(slot + CK_MN + j * 640 + n * 40 + 8 * g);
;     const u32x2 ylo = ck_ld8(slot + CK_MY + n * 72 + 8 * g), yhi = ck_ld8(slot + CK_MY + n * 72 + 8 * g + 32);
; #pragma unroll
;     for (int kb = 0; kb < 4; ++kb) { const LAS unsigned char* p = slot + CK_BK + (16 * kb + n) * 72 + 8 * g; blo[kb] = ck_ld8(p); bhi[kb] = ck_ld8(p + 32); gm[kb] = *(const LAS f32x4*)(slot + CK_GM + (16 * kb + 4 * g) * 4); }
;     f32x4 xacc[2] = {zero4, zero4};
; #pragma unroll
;     for (int ks = 0; ks < 2; ++ks) {
;         const pg8::bf16x8 Bs = ck_frag(pkc(sacc[2 * ks][0], sacc[2 * ks][1]), pkc(sacc[2 * ks][2], sacc[2 * ks][3]), pkc(sacc[2 * ks + 1][0], sacc[2 * ks + 1][1]), pkc(sacc[2 * ks + 1][2], sacc[2 * ks + 1][3]));
; #pragma unroll
;         for (int mt = 0; mt < 2; ++mt) xacc[mt] = __builtin_amdgcn_mfma_f32_16x16x32_bf16(ck_frag(qlo[ks][mt].x, qlo[ks][mt].y, qhi[ks][mt].x, qhi[ks][mt].y), Bs, xacc[mt], 0, 0, 0);
;     }
;     f32x4 Z = __builtin_amdgcn_mfma_f32_16x16x32_bf16(ck_frag(0u, 0u, mk.x, mk.y), ck_frag(0u, 0u, vq.x, vq.y), xacc[0], 0, 0, 0);
; #pragma unroll
;     for (int j = 0; j < 4; ++j) Z = __builtin_amdgcn_mfma_f32_16x16x32_bf16(ck_frag(mn[j].x, mn[j].y, 0u, 0u), ck_frag(pkc(Z[0], Z[1]), pkc(Z[2], Z[3]), vq.x, vq.y), Z, 0, 0, 0);
;     const pg8::bf16x8 UV = ck_frag(pkc(Z[0], Z[1]), pkc(Z[2], Z[3]), vq.x, vq.y);
;     { const f32x4 y = __builtin_amdgcn_mfma_f32_16x16x32_bf16(ck_frag(ylo.x, ylo.y, yhi.x, yhi.y), UV, xacc[1], 0, 0, 0);
;       yout = y; vout = vq; dout = *(const LAS f32x4*)(slot + CK_DOT + 16 * g);
; #pragma unroll
	v_mfma_f32_16x16x32_bf16 v[48:51], v[92:95], v[44:47], v[48:51]
	v_mov_b32_e32 v92, v102
	v_mov_b32_e32 v93, v103
	v_mov_b32_e32 v94, v129
	v_mov_b32_e32 v95, v129
	v_mov_b32_e32 v99, v129
	s_nop 2
	v_cvt_pk_bf16_f32 v44, v48, v49
	v_cvt_pk_bf16_f32 v45, v50, v51
	v_add_u32_e32 v32, v32, v172
	v_add_u32_e32 v32, 0x1000, v32
	v_mfma_f32_16x16x32_bf16 v[48:51], v[92:95], v[44:47], v[48:51]
	v_mov_b32_e32 v92, v106
	v_mov_b32_e32 v93, v107
	ds_read2_b64 v[100:103], v32 offset0:32 offset1:36
	s_lshl_b32 s7, s7, 9
	s_add_i32 s7, s7, 0
	s_nop 2
	v_cvt_pk_bf16_f32 v44, v48, v49
	v_cvt_pk_bf16_f32 v45, v50, v51
	s_add_i32 s7, s7, 0x24800
	v_add_u32_e32 v106, s7, v173
	v_mfma_f32_16x16x32_bf16 v[48:51], v[96:99], v[44:47], v[48:51]
	s_nop 7
	v_cvt_pk_bf16_f32 v44, v48, v49
	v_cvt_pk_bf16_f32 v45, v50, v51
	s_nop 1
	v_mfma_f32_16x16x32_bf16 v[48:51], v[92:95], v[44:47], v[48:51]
	ds_read_b128 v[96:99], v33 offset:16000
	ds_read_b128 v[92:95], v33 offset:16064
	s_nop 5
	v_cvt_pk_bf16_f32 v44, v48, v49
	v_cvt_pk_bf16_f32 v45, v50, v51
	s_waitcnt lgkmcnt(9)
	s_nop 0
	v_mfma_f32_16x16x32_bf16 v[48:51], v[108:111], v[44:47], v[48:51]
	s_nop 7
	v_cvt_pk_bf16_f32 v44, v48, v49
	v_cvt_pk_bf16_f32 v45, v50, v51
	ds_read_b128 v[48:51], v33 offset:16128
	s_waitcnt lgkmcnt(9)
	v_mfma_f32_16x16x32_bf16 v[52:55], v[112:115], v[44:47], v[52:55]
	s_waitcnt lgkmcnt(3)
	v_mfma_f32_16x16x32_bf16 v[64:67], v[80:83], v[44:47], v[64:67]
	v_mfma_f32_16x16x32_bf16 v[68:71], v[88:91], v[44:47], v[68:71]
	s_waitcnt lgkmcnt(0)
	v_mfma_f32_16x16x32_bf16 v[60:63], v[84:87], v[44:47], v[60:63]
	s_waitcnt lgkmcnt(0)
	v_mfma_f32_16x16x32_bf16 v[56:59], v[100:103], v[44:47], v[56:59]
	s_nop 0
	v_mul_f32_e32 v105, v52, v52
	v_mov_b32_dpp v32, v52 quad_perm:[1,0,3,2] row_mask:0xf bank_mask:0xf bound_ctrl:1
	v_mov_b32_e32 v104, v52
	v_mov_b32_dpp v33, v105 quad_perm:[1,0,3,2] row_mask:0xf bank_mask:0xf bound_ctrl:1
	v_pk_add_f32 v[32:33], v[104:105], v[32:33]
	s_nop 1
	v_mov_b32_dpp v104, v32 quad_perm:[2,3,0,1] row_mask:0xf bank_mask:0xf bound_ctrl:1
	v_mov_b32_dpp v105, v33 quad_perm:[2,3,0,1] row_mask:0xf bank_mask:0xf bound_ctrl:1
	v_pk_add_f32 v[32:33], v[32:33], v[104:105]
	s_nop 1
	v_mov_b32_dpp v104, v32 row_half_mirror row_mask:0xf bank_mask:0xf bound_ctrl:1
	v_mov_b32_dpp v105, v33 row_half_mirror row_mask:0xf bank_mask:0xf bound_ctrl:1
	v_pk_add_f32 v[32:33], v[32:33], v[104:105]
	s_nop 1
	v_mov_b32_dpp v104, v32 row_mirror row_mask:0xf bank_mask:0xf bound_ctrl:1
	v_mov_b32_dpp v105, v33 row_mirror row_mask:0xf bank_mask:0xf bound_ctrl:1
	s_and_saveexec_b64 s[34:35], s[40:41]
	v_pk_add_f32 v[32:33], v[32:33], v[104:105]
	ds_write_b64 v106, v[32:33]
	s_or_b64 exec, exec, s[34:35]
	v_mul_f32_e32 v105, v53, v53
	v_mov_b32_dpp v32, v53 quad_perm:[1,0,3,2] row_mask:0xf bank_mask:0xf bound_ctrl:1
	v_mov_b32_e32 v104, v53
	v_mov_b32_dpp v33, v105 quad_perm:[1,0,3,2] row_mask:0xf bank_mask:0xf bound_ctrl:1
	v_pk_add_f32 v[32:33], v[104:105], v[32:33]
	s_nop 1
	v_mov_b32_dpp v104, v32 quad_perm:[2,3,0,1] row_mask:0xf bank_mask:0xf bound_ctrl:1
	v_mov_b32_dpp v105, v33 quad_perm:[2,3,0,1] row_mask:0xf bank_mask:0xf bound_ctrl:1
	v_pk_add_f32 v[32:33], v[32:33], v[104:105]
	s_nop 1
	v_mov_b32_dpp v104, v32 row_half_mirror row_mask:0xf bank_mask:0xf bound_ctrl:1
	v_mov_b32_dpp v105, v33 row_half_mirror row_mask:0xf bank_mask:0xf bound_ctrl:1
	v_pk_add_f32 v[32:33], v[32:33], v[104:105]
	s_nop 1
	v_mov_b32_dpp v104, v32 row_mirror row_mask:0xf bank_mask:0xf bound_ctrl:1
	v_mov_b32_dpp v105, v33 row_mirror row_mask:0xf bank_mask:0xf bound_ctrl:1
	s_and_saveexec_b64 s[34:35], s[40:41]
	v_pk_add_f32 v[32:33], v[32:33], v[104:105]
	ds_write_b64 v106, v[32:33] offset:32
	s_or_b64 exec, exec, s[34:35]
	v_mul_f32_e32 v105, v54, v54
	v_mov_b32_dpp v32, v54 quad_perm:[1,0,3,2] row_mask:0xf bank_mask:0xf bound_ctrl:1
	v_mov_b32_e32 v104, v54
	v_mov_b32_dpp v33, v105 quad_perm:[1,0,3,2] row_mask:0xf bank_mask:0xf bound_ctrl:1
	v_pk_add_f32 v[32:33], v[104:105], v[32:33]
	s_nop 1
	v_mov_b32_dpp v104, v32 quad_perm:[2,3,0,1] row_mask:0xf bank_mask:0xf bound_ctrl:1
	v_mov_b32_dpp v105, v33 quad_perm:[2,3,0,1] row_mask:0xf bank_mask:0xf bound_ctrl:1
	v_pk_add_f32 v[32:33], v[32:33], v[104:105]
	s_nop 1
	v_mov_b32_dpp v104, v32 row_half_mirror row_mask:0xf bank_mask:0xf bound_ctrl:1
	v_mov_b32_dpp v105, v33 row_half_mirror row_mask:0xf bank_mask:0xf bound_ctrl:1
	v_pk_add_f32 v[32:33], v[32:33], v[104:105]
	s_nop 1
	v_mov_b32_dpp v104, v32 row_mirror row_mask:0xf bank_mask:0xf bound_ctrl:1
	v_mov_b32_dpp v105, v33 row_mirror row_mask:0xf bank_mask:0xf bound_ctrl:1
	s_and_saveexec_b64 s[34:35], s[40:41]
	v_pk_add_f32 v[32:33], v[32:33], v[104:105]
	ds_write_b64 v106, v[32:33] offset:64
	s_or_b64 exec, exec, s[34:35]
	v_mul_f32_e32 v105, v55, v55
	v_mov_b32_dpp v32, v55 quad_perm:[1,0,3,2] row_mask:0xf bank_mask:0xf bound_ctrl:1
	v_mov_b32_e32 v104, v55
	v_mov_b32_dpp v33, v105 quad_perm:[1,0,3,2] row_mask:0xf bank_mask:0xf bound_ctrl:1
	v_pk_add_f32 v[32:33], v[104:105], v[32:33]
	s_nop 1
	v_mov_b32_dpp v104, v32 quad_perm:[2,3,0,1] row_mask:0xf bank_mask:0xf bound_ctrl:1
	v_mov_b32_dpp v105, v33 quad_perm:[2,3,0,1] row_mask:0xf bank_mask:0xf bound_ctrl:1
	v_pk_add_f32 v[32:33], v[32:33], v[104:105]
	s_nop 1
	v_mov_b32_dpp v104, v32 row_half_mirror row_mask:0xf bank_mask:0xf bound_ctrl:1
	v_mov_b32_dpp v105, v33 row_half_mirror row_mask:0xf bank_mask:0xf bound_ctrl:1
	v_pk_add_f32 v[32:33], v[32:33], v[104:105]
	s_nop 1
	v_mov_b32_dpp v104, v32 row_mirror row_mask:0xf bank_mask:0xf bound_ctrl:1
	v_mov_b32_dpp v105, v33 row_mirror row_mask:0xf bank_mask:0xf bound_ctrl:1
	s_and_saveexec_b64 s[34:35], s[40:41]
	v_pk_add_f32 v[32:33], v[32:33], v[104:105]
	ds_write_b64 v106, v[32:33] offset:96
	s_or_b64 exec, exec, s[34:35]
	v_add_co_u32_e32 v32, vcc, 0x10000, v158
	v_addc_co_u32_e32 v33, vcc, 0, v159, vcc
	v_add_co_u32_e32 v80, vcc, 0x11000, v158
	s_nop 0
	v_addc_co_u32_e32 v81, vcc, 0, v159, vcc
	s_or_b32 s7, s2, 2
	s_lshl_b32 s33, s7, 14
	s_add_i32 s33, s33, 0
	v_mov_b32_e32 v122, v129
	v_add_co_u32_e32 v44, vcc, 0x12000, v158
	v_mov_b32_e32 v123, v129
	s_nop 0
	v_addc_co_u32_e32 v45, vcc, 0, v159, vcc
	v_add_co_u32_e32 v82, vcc, 0x13000, v158
	s_lshl_b32 s7, s7, 9
	s_nop 0
	v_addc_co_u32_e32 v83, vcc, 0, v159, vcc
	global_load_ushort v236, v[32:33], off
	global_load_ushort v237, v[80:81], off
	global_load_ushort v238, v[44:45], off
	global_load_ushort v239, v[82:83], off
	v_add_u32_e32 v32, s33, v166
	v_add_u32_e32 v33, v32, v167
	v_pk_mul_f32 v[82:83], v[78:79], v[70:71]
	v_pk_mul_f32 v[80:81], v[76:77], v[68:69]
	v_pk_mul_f32 v[78:79], v[74:75], v[66:67]
	v_pk_mul_f32 v[76:77], v[72:73], v[64:65]
	s_waitcnt lgkmcnt(2)
; __device__ __forceinline__ void ck_consume(const LAS unsigned char* slot, f32x4 (&sacc)[4], LAS unsigned char* st  , int lane, int cw, f32x4& yout, u32x2& vout, f32x4& dout) {
;     const int n = lane & 15, g = lane >> 4;
;     const f32x4 zero4 = {0.f, 0.f, 0.f, 0.f};
;     u32x2 qlo[2][2], qhi[2][2], mn[4], blo[4], bhi[4]; f32x4 gm[4];
; #pragma unroll
;     for (int ks = 0; ks < 2; ++ks)
; #pragma unroll
;         for (int mt = 0; mt < 2; ++mt) { const LAS unsigned char* p = slot + CK_QR + (16 * mt + n) * 136 + (32 * ks + 4 * g) * 2; qlo[ks][mt] = ck_ld8(p); qhi[ks][mt] = ck_ld8(p + 32); }
;     const u32x2 vq = ck_ld8(slot + CK_VT + (16 * cw + n) * 40 + 8 * g);
;     const u32x2 mk = ck_ld8(slot + CK_MK + n * 40 + 8 * g);
; #pragma unroll
;     for (int j = 0; j < 4; ++j) mn[j] = ck_ld8(slot + CK_MN + j * 640 + n * 40 + 8 * g);
;     const u32x2 ylo = ck_ld8(slot + CK_MY + n * 72 + 8 * g), yhi = ck_ld8(slot + CK_MY + n * 72 + 8 * g + 32);
; #pragma unroll
;     for (int kb = 0; kb < 4; ++kb) { const LAS unsigned char* p = slot + CK_BK + (16 * kb + n) * 72 + 8 * g; blo[kb] = ck_ld8(p); bhi[kb] = ck_ld8(p + 32); gm[kb] = *(const LAS f32x4*)(slot + CK_GM + (16 * kb + 4 * g) * 4); }
;     f32x4 xacc[2] = {zero4, zero4};
; #pragma unroll
;     for (int ks = 0; ks < 2; ++ks) {
;         const pg8::bf16x8 Bs = ck_frag(pkc(sacc[2 * ks][0], sacc[2 * ks][1]), pkc(sacc[2 * ks][2], sacc[2 * ks][3]), pkc(sacc[2 * ks + 1][0], sacc[2 * ks + 1][1]), pkc(sacc[2 * ks + 1][2], sacc[2 * ks + 1][3]));
; #pragma unroll
;         for (int mt = 0; mt < 2; ++mt) xacc[mt] = __builtin_amdgcn_mfma_f32_16x16x32_bf16(ck_frag(qlo[ks][mt].x, qlo[ks][mt].y, qhi[ks][mt].x, qhi[ks][mt].y), Bs, xacc[mt], 0, 0, 0);
;     }
;     f32x4 Z = __builtin_amdgcn_mfma_f32_16x16x32_bf16(ck_frag(0u, 0u, mk.x, mk.y), ck_frag(0u, 0u, vq.x, vq.y), xacc[0], 0, 0, 0);
; #pragma unroll
;     for (int j = 0; j < 4; ++j) Z = __builtin_amdgcn_mfma_f32_16x16x32_bf16(ck_frag(mn[j].x, mn[j].y, 0u, 0u), ck_frag(pkc(Z[0], Z[1]), pkc(Z[2], Z[3]), vq.x, vq.y), Z, 0, 0, 0);
;     const pg8::bf16x8 UV = ck_frag(pkc(Z[0], Z[1]), pkc(Z[2], Z[3]), vq.x, vq.y);
;     { const f32x4 y = __builtin_amdgcn_mfma_f32_16x16x32_bf16(ck_frag(ylo.x, ylo.y, yhi.x, yhi.y), UV, xacc[1], 0, 0, 0);
;       yout = y; vout = vq; dout = *(const LAS f32x4*)(slot + CK_DOT + 16 * g);
; #pragma unroll
	v_pk_mul_f32 v[74:75], v[98:99], v[62:63]
	v_pk_mul_f32 v[72:73], v[96:97], v[60:61]
	ds_read2_b64 v[60:63], v33 offset1:4
	v_add_u32_e32 v44, 0x800, v33
	ds_read2_b64 v[64:67], v44 offset0:16 offset1:20
	ds_read2_b64 v[104:107], v33 offset0:8 offset1:12
	ds_read2_b64 v[108:111], v44 offset0:24 offset1:28
	v_add_u32_e32 v44, v32, v169
	v_add_u32_e32 v45, 0x2800, v44
	ds_read2_b64 v[112:115], v45 offset0:160 offset1:240
	v_cvt_pk_bf16_f32 v214, v80, v81
	v_cvt_pk_bf16_f32 v215, v82, v83
	v_cvt_pk_bf16_f32 v216, v76, v77
	v_cvt_pk_bf16_f32 v217, v78, v79
	s_waitcnt lgkmcnt(6)
	v_pk_mul_f32 v[70:71], v[94:95], v[58:59]
	v_pk_mul_f32 v[68:69], v[92:93], v[56:57]
	s_waitcnt lgkmcnt(4)
	v_mfma_f32_16x16x32_bf16 v[60:63], v[60:63], v[214:217], 0
	v_add_u32_e32 v45, 0x3000, v44
	v_add_u32_e32 v33, v32, v168
	ds_read2_b64 v[116:119], v45 offset0:64 offset1:144
	ds_read_b64 v[58:59], v33 offset:8960
	ds_read_b64 v[120:121], v44 offset:14080
	s_waitcnt lgkmcnt(6)
	v_mfma_f32_16x16x32_bf16 v[64:67], v[64:67], v[214:217], 0
	v_cvt_pk_bf16_f32 v214, v72, v73
	v_cvt_pk_bf16_f32 v215, v74, v75
	v_cvt_pk_bf16_f32 v216, v68, v69
	v_cvt_pk_bf16_f32 v217, v70, v71
	v_mov_b32_e32 v56, v129
	v_mov_b32_e32 v57, v129
	s_waitcnt lgkmcnt(5)
	v_mfma_f32_16x16x32_bf16 v[60:63], v[104:107], v[214:217], v[60:63]
	v_mov_b32_e32 v104, v129
	v_mov_b32_e32 v105, v129
	s_waitcnt lgkmcnt(3)
	v_mov_b32_e32 v106, v112
	v_mov_b32_e32 v107, v113
	v_mfma_f32_16x16x32_bf16 v[64:67], v[108:111], v[214:217], v[64:67]
	s_waitcnt lgkmcnt(2)
	v_mov_b32_e32 v108, v116
	v_mov_b32_e32 v109, v117
	v_mov_b32_e32 v110, v129
	s_waitcnt lgkmcnt(1)
	v_mfma_f32_16x16x32_bf16 v[60:63], v[104:107], v[56:59], v[60:63]
	v_mov_b32_e32 v104, v114
	v_mov_b32_e32 v105, v115
	v_mov_b32_e32 v106, v129
	v_mov_b32_e32 v107, v129
	v_mov_b32_e32 v111, v129
	s_nop 2
	v_cvt_pk_bf16_f32 v56, v60, v61
	v_cvt_pk_bf16_f32 v57, v62, v63
	v_add3_u32 v33, s33, v170, v166
	v_add_u32_e32 v33, 0x3800, v33
	v_mfma_f32_16x16x32_bf16 v[60:63], v[104:107], v[56:59], v[60:63]
	v_mov_b32_e32 v104, v118
	v_mov_b32_e32 v105, v119
	ds_read2_b64 v[124:127], v33 offset0:48 offset1:52
	v_add_u32_e32 v44, v32, v170
	v_add_u32_e32 v45, 0x1000, v44
	s_nop 2
	v_cvt_pk_bf16_f32 v56, v60, v61
	v_cvt_pk_bf16_f32 v57, v62, v63
	v_add_u32_e32 v32, v32, v172
	v_add_u32_e32 v33, s33, v171
	v_mfma_f32_16x16x32_bf16 v[60:63], v[108:111], v[56:59], v[60:63]
	ds_read2_b64 v[100:103], v45 offset0:32 offset1:36
	ds_read2_b64 v[92:95], v45 offset0:176 offset1:180
	v_add_u32_e32 v44, 0x1800, v44
	v_add_u32_e32 v32, 0x1000, v32
	ds_read_b128 v[88:91], v33 offset:15872
	ds_read_b128 v[84:87], v33 offset:15936
	s_nop 1
	v_cvt_pk_bf16_f32 v56, v60, v61
	v_cvt_pk_bf16_f32 v57, v62, v63
	ds_read2_b64 v[96:99], v44 offset0:64 offset1:68
	ds_read2_b64 v[112:115], v32 offset0:32 offset1:36
	v_mfma_f32_16x16x32_bf16 v[60:63], v[104:107], v[56:59], v[60:63]
	ds_read_b128 v[108:111], v33 offset:16000
	ds_read_b128 v[104:107], v33 offset:16064
	s_add_i32 s7, s7, 0
	s_add_i32 s7, s7, 0x24800
	v_add_u32_e32 v116, s7, v173
	s_nop 2
	v_cvt_pk_bf16_f32 v56, v60, v61
	v_cvt_pk_bf16_f32 v57, v62, v63
	s_waitcnt lgkmcnt(9)
	s_nop 0
	v_mfma_f32_16x16x32_bf16 v[60:63], v[120:123], v[56:59], v[60:63]
	s_nop 7
	v_cvt_pk_bf16_f32 v56, v60, v61
	v_cvt_pk_bf16_f32 v57, v62, v63
	ds_read_b128 v[60:63], v33 offset:16128
	s_waitcnt lgkmcnt(9)
	v_mfma_f32_16x16x32_bf16 v[64:67], v[124:127], v[56:59], v[64:67]
	s_waitcnt lgkmcnt(3)
	v_mfma_f32_16x16x32_bf16 v[76:79], v[92:95], v[56:59], v[76:79]
	v_mfma_f32_16x16x32_bf16 v[80:83], v[100:103], v[56:59], v[80:83]
	s_waitcnt lgkmcnt(0)
	v_mfma_f32_16x16x32_bf16 v[72:75], v[96:99], v[56:59], v[72:75]
	s_waitcnt lgkmcnt(0)
	v_mfma_f32_16x16x32_bf16 v[68:71], v[112:115], v[56:59], v[68:71]
	s_nop 0
	v_mul_f32_e32 v45, v64, v64
	v_mov_b32_dpp v32, v64 quad_perm:[1,0,3,2] row_mask:0xf bank_mask:0xf bound_ctrl:1
	v_mov_b32_e32 v44, v64
	v_mov_b32_dpp v33, v45 quad_perm:[1,0,3,2] row_mask:0xf bank_mask:0xf bound_ctrl:1
	v_pk_add_f32 v[32:33], v[44:45], v[32:33]
	s_nop 1
	v_mov_b32_dpp v44, v32 quad_perm:[2,3,0,1] row_mask:0xf bank_mask:0xf bound_ctrl:1
	v_mov_b32_dpp v45, v33 quad_perm:[2,3,0,1] row_mask:0xf bank_mask:0xf bound_ctrl:1
	v_pk_add_f32 v[32:33], v[32:33], v[44:45]
	s_nop 1
	v_mov_b32_dpp v44, v32 row_half_mirror row_mask:0xf bank_mask:0xf bound_ctrl:1
	v_mov_b32_dpp v45, v33 row_half_mirror row_mask:0xf bank_mask:0xf bound_ctrl:1
	v_pk_add_f32 v[32:33], v[32:33], v[44:45]
	s_nop 1
	v_mov_b32_dpp v44, v32 row_mirror row_mask:0xf bank_mask:0xf bound_ctrl:1
	v_mov_b32_dpp v45, v33 row_mirror row_mask:0xf bank_mask:0xf bound_ctrl:1
	s_and_saveexec_b64 s[34:35], s[40:41]
	v_pk_add_f32 v[32:33], v[32:33], v[44:45]
	ds_write_b64 v116, v[32:33]
	s_or_b64 exec, exec, s[34:35]
	v_mul_f32_e32 v45, v65, v65
	v_mov_b32_dpp v32, v65 quad_perm:[1,0,3,2] row_mask:0xf bank_mask:0xf bound_ctrl:1
	v_mov_b32_e32 v44, v65
	v_mov_b32_dpp v33, v45 quad_perm:[1,0,3,2] row_mask:0xf bank_mask:0xf bound_ctrl:1
	v_pk_add_f32 v[32:33], v[44:45], v[32:33]
	s_nop 1
	v_mov_b32_dpp v44, v32 quad_perm:[2,3,0,1] row_mask:0xf bank_mask:0xf bound_ctrl:1
	v_mov_b32_dpp v45, v33 quad_perm:[2,3,0,1] row_mask:0xf bank_mask:0xf bound_ctrl:1
	v_pk_add_f32 v[32:33], v[32:33], v[44:45]
	s_nop 1
	v_mov_b32_dpp v44, v32 row_half_mirror row_mask:0xf bank_mask:0xf bound_ctrl:1
	v_mov_b32_dpp v45, v33 row_half_mirror row_mask:0xf bank_mask:0xf bound_ctrl:1
	v_pk_add_f32 v[32:33], v[32:33], v[44:45]
	s_nop 1
	v_mov_b32_dpp v44, v32 row_mirror row_mask:0xf bank_mask:0xf bound_ctrl:1
	v_mov_b32_dpp v45, v33 row_mirror row_mask:0xf bank_mask:0xf bound_ctrl:1
; __device__ __forceinline__ void ck_consume(const LAS unsigned char* slot, f32x4 (&sacc)[4], LAS unsigned char* st  , int lane, int cw, f32x4& yout, u32x2& vout, f32x4& dout) {
;     const int n = lane & 15, g = lane >> 4;
;     const f32x4 zero4 = {0.f, 0.f, 0.f, 0.f};
;     u32x2 qlo[2][2], qhi[2][2], mn[4], blo[4], bhi[4]; f32x4 gm[4];
; #pragma unroll
;     for (int ks = 0; ks < 2; ++ks)
; #pragma unroll
;         for (int mt = 0; mt < 2; ++mt) { const LAS unsigned char* p = slot + CK_QR + (16 * mt + n) * 136 + (32 * ks + 4 * g) * 2; qlo[ks][mt] = ck_ld8(p); qhi[ks][mt] = ck_ld8(p + 32); }
;     const u32x2 vq = ck_ld8(slot + CK_VT + (16 * cw + n) * 40 + 8 * g);
;     const u32x2 mk = ck_ld8(slot + CK_MK + n * 40 + 8 * g);
; #pragma unroll
;     for (int j = 0; j < 4; ++j) mn[j] = ck_ld8(slot + CK_MN + j * 640 + n * 40 + 8 * g);
;     const u32x2 ylo = ck_ld8(slot + CK_MY + n * 72 + 8 * g), yhi = ck_ld8(slot + CK_MY + n * 72 + 8 * g + 32);
; #pragma unroll
;     for (int kb = 0; kb < 4; ++kb) { const LAS unsigned char* p = slot + CK_BK + (16 * kb + n) * 72 + 8 * g; blo[kb] = ck_ld8(p); bhi[kb] = ck_ld8(p + 32); gm[kb] = *(const LAS f32x4*)(slot + CK_GM + (16 * kb + 4 * g) * 4); }
;     f32x4 xacc[2] = {zero4, zero4};
; #pragma unroll
;     for (int ks = 0; ks < 2; ++ks) {
;         const pg8::bf16x8 Bs = ck_frag(pkc(sacc[2 * ks][0], sacc[2 * ks][1]), pkc(sacc[2 * ks][2], sacc[2 * ks][3]), pkc(sacc[2 * ks + 1][0], sacc[2 * ks + 1][1]), pkc(sacc[2 * ks + 1][2], sacc[2 * ks + 1][3]));
; #pragma unroll
;         for (int mt = 0; mt < 2; ++mt) xacc[mt] = __builtin_amdgcn_mfma_f32_16x16x32_bf16(ck_frag(qlo[ks][mt].x, qlo[ks][mt].y, qhi[ks][mt].x, qhi[ks][mt].y), Bs, xacc[mt], 0, 0, 0);
;     }
;     f32x4 Z = __builtin_amdgcn_mfma_f32_16x16x32_bf16(ck_frag(0u, 0u, mk.x, mk.y), ck_frag(0u, 0u, vq.x, vq.y), xacc[0], 0, 0, 0);
; #pragma unroll
;     for (int j = 0; j < 4; ++j) Z = __builtin_amdgcn_mfma_f32_16x16x32_bf16(ck_frag(mn[j].x, mn[j].y, 0u, 0u), ck_frag(pkc(Z[0], Z[1]), pkc(Z[2], Z[3]), vq.x, vq.y), Z, 0, 0, 0);
;     const pg8::bf16x8 UV = ck_frag(pkc(Z[0], Z[1]), pkc(Z[2], Z[3]), vq.x, vq.y);
;     { const f32x4 y = __builtin_amdgcn_mfma_f32_16x16x32_bf16(ck_frag(ylo.x, ylo.y, yhi.x, yhi.y), UV, xacc[1], 0, 0, 0);
;       yout = y; vout = vq; dout = *(const LAS f32x4*)(slot + CK_DOT + 16 * g);
; #pragma unroll
	s_and_saveexec_b64 s[34:35], s[40:41]
	v_pk_add_f32 v[32:33], v[32:33], v[44:45]
	ds_write_b64 v116, v[32:33] offset:32
	s_or_b64 exec, exec, s[34:35]
	v_mul_f32_e32 v45, v66, v66
	v_mov_b32_dpp v32, v66 quad_perm:[1,0,3,2] row_mask:0xf bank_mask:0xf bound_ctrl:1
	v_mov_b32_e32 v44, v66
	v_mov_b32_dpp v33, v45 quad_perm:[1,0,3,2] row_mask:0xf bank_mask:0xf bound_ctrl:1
	v_pk_add_f32 v[32:33], v[44:45], v[32:33]
	s_nop 1
	v_mov_b32_dpp v44, v32 quad_perm:[2,3,0,1] row_mask:0xf bank_mask:0xf bound_ctrl:1
	v_mov_b32_dpp v45, v33 quad_perm:[2,3,0,1] row_mask:0xf bank_mask:0xf bound_ctrl:1
	v_pk_add_f32 v[32:33], v[32:33], v[44:45]
	s_nop 1
	v_mov_b32_dpp v44, v32 row_half_mirror row_mask:0xf bank_mask:0xf bound_ctrl:1
	v_mov_b32_dpp v45, v33 row_half_mirror row_mask:0xf bank_mask:0xf bound_ctrl:1
	v_pk_add_f32 v[32:33], v[32:33], v[44:45]
	s_nop 1
	v_mov_b32_dpp v44, v32 row_mirror row_mask:0xf bank_mask:0xf bound_ctrl:1
	v_mov_b32_dpp v45, v33 row_mirror row_mask:0xf bank_mask:0xf bound_ctrl:1
	s_and_saveexec_b64 s[34:35], s[40:41]
	v_pk_add_f32 v[32:33], v[32:33], v[44:45]
	ds_write_b64 v116, v[32:33] offset:64
	s_or_b64 exec, exec, s[34:35]
	v_mul_f32_e32 v45, v67, v67
	v_mov_b32_dpp v32, v67 quad_perm:[1,0,3,2] row_mask:0xf bank_mask:0xf bound_ctrl:1
	v_mov_b32_e32 v44, v67
	v_mov_b32_dpp v33, v45 quad_perm:[1,0,3,2] row_mask:0xf bank_mask:0xf bound_ctrl:1
	v_pk_add_f32 v[32:33], v[44:45], v[32:33]
	s_nop 1
	v_mov_b32_dpp v44, v32 quad_perm:[2,3,0,1] row_mask:0xf bank_mask:0xf bound_ctrl:1
	v_mov_b32_dpp v45, v33 quad_perm:[2,3,0,1] row_mask:0xf bank_mask:0xf bound_ctrl:1
	v_pk_add_f32 v[32:33], v[32:33], v[44:45]
	s_nop 1
	v_mov_b32_dpp v44, v32 row_half_mirror row_mask:0xf bank_mask:0xf bound_ctrl:1
	v_mov_b32_dpp v45, v33 row_half_mirror row_mask:0xf bank_mask:0xf bound_ctrl:1
	v_pk_add_f32 v[32:33], v[32:33], v[44:45]
	s_nop 1
	v_mov_b32_dpp v44, v32 row_mirror row_mask:0xf bank_mask:0xf bound_ctrl:1
	v_mov_b32_dpp v45, v33 row_mirror row_mask:0xf bank_mask:0xf bound_ctrl:1
	s_and_saveexec_b64 s[34:35], s[40:41]
	v_pk_add_f32 v[32:33], v[32:33], v[44:45]
	ds_write_b64 v116, v[32:33] offset:96
	s_or_b64 exec, exec, s[34:35]
	v_add_co_u32_e32 v32, vcc, 0x20000, v158
	v_addc_co_u32_e32 v33, vcc, 0, v159, vcc
	v_add_co_u32_e32 v44, vcc, 0x21000, v158
	s_nop 0
	v_addc_co_u32_e32 v45, vcc, 0, v159, vcc
	v_add_co_u32_e32 v92, vcc, 0x22000, v158
	v_addc_co_u32_e32 v93, vcc, 0, v159, vcc
	v_add_co_u32_e32 v94, vcc, 0x23000, v158
	v_addc_co_u32_e32 v95, vcc, 0, v159, vcc
	global_load_ushort v56, v[32:33], off
	global_load_ushort v57, v[44:45], off
	global_load_ushort v240, v[92:93], off
	global_load_ushort v241, v[94:95], off
	s_or_b32 s2, s2, 3
	s_lshl_b32 s7, s2, 14
	s_add_i32 s7, s7, 0
	v_add_u32_e32 v32, s7, v166
	v_add_u32_e32 v33, v32, v167
	v_pk_mul_f32 v[94:95], v[90:91], v[82:83]
	v_pk_mul_f32 v[92:93], v[88:89], v[80:81]
	v_pk_mul_f32 v[90:91], v[86:87], v[78:79]
	v_pk_mul_f32 v[88:89], v[84:85], v[76:77]
	s_waitcnt lgkmcnt(2)
	v_pk_mul_f32 v[86:87], v[110:111], v[74:75]
	v_pk_mul_f32 v[84:85], v[108:109], v[72:73]
	ds_read2_b64 v[72:75], v33 offset1:4
	v_add_u32_e32 v44, 0x800, v33
	ds_read2_b64 v[76:79], v44 offset0:16 offset1:20
	ds_read2_b64 v[116:119], v33 offset0:8 offset1:12
	ds_read2_b64 v[120:123], v44 offset0:24 offset1:28
	v_add_u32_e32 v44, v32, v169
	v_add_u32_e32 v45, 0x2800, v44
	ds_read2_b64 v[124:127], v45 offset0:160 offset1:240
	v_cvt_pk_bf16_f32 v250, v92, v93
	v_cvt_pk_bf16_f32 v251, v94, v95
	v_cvt_pk_bf16_f32 v252, v88, v89
	v_cvt_pk_bf16_f32 v253, v90, v91
	s_waitcnt lgkmcnt(6)
	v_pk_mul_f32 v[82:83], v[106:107], v[70:71]
	v_pk_mul_f32 v[80:81], v[104:105], v[68:69]
	s_waitcnt lgkmcnt(4)
	v_mfma_f32_16x16x32_bf16 v[72:75], v[72:75], v[250:253], 0
	v_add_u32_e32 v45, 0x3000, v44
	v_add_u32_e32 v33, v32, v168
	ds_read2_b64 v[214:217], v45 offset0:64 offset1:144
	ds_read_b64 v[70:71], v33 offset:8960
	ds_read_b64 v[242:243], v44 offset:14080
	s_waitcnt lgkmcnt(6)
	v_mfma_f32_16x16x32_bf16 v[76:79], v[76:79], v[250:253], 0
	v_cvt_pk_bf16_f32 v250, v84, v85
	v_cvt_pk_bf16_f32 v251, v86, v87
	v_cvt_pk_bf16_f32 v252, v80, v81
	v_cvt_pk_bf16_f32 v253, v82, v83
	v_mov_b32_e32 v68, v129
	v_mov_b32_e32 v69, v129
	s_waitcnt lgkmcnt(5)
	v_mfma_f32_16x16x32_bf16 v[72:75], v[116:119], v[250:253], v[72:75]
	v_mov_b32_e32 v116, v129
	v_mov_b32_e32 v117, v129
	s_waitcnt lgkmcnt(3)
	v_mov_b32_e32 v118, v124
	v_mov_b32_e32 v119, v125
	v_mfma_f32_16x16x32_bf16 v[76:79], v[120:123], v[250:253], v[76:79]
	s_waitcnt lgkmcnt(2)
	v_mov_b32_e32 v120, v214
	v_mov_b32_e32 v121, v215
	v_mov_b32_e32 v122, v129
	s_waitcnt lgkmcnt(1)
	v_mfma_f32_16x16x32_bf16 v[72:75], v[116:119], v[68:71], v[72:75]
	v_mov_b32_e32 v116, v126
	v_mov_b32_e32 v117, v127
	v_mov_b32_e32 v118, v129
	v_mov_b32_e32 v119, v129
	v_mov_b32_e32 v123, v129
	s_nop 2
	v_cvt_pk_bf16_f32 v68, v72, v73
	v_cvt_pk_bf16_f32 v69, v74, v75
	v_add3_u32 v33, s7, v170, v166
	v_add_u32_e32 v33, 0x3800, v33
	v_mfma_f32_16x16x32_bf16 v[72:75], v[116:119], v[68:71], v[72:75]
	v_mov_b32_e32 v116, v216
	v_mov_b32_e32 v117, v217
	v_mov_b32_e32 v244, v129
	v_mov_b32_e32 v245, v129
	ds_read2_b64 v[246:249], v33 offset0:48 offset1:52
	s_nop 2
	v_cvt_pk_bf16_f32 v68, v72, v73
	v_cvt_pk_bf16_f32 v69, v74, v75
	v_add_u32_e32 v44, v32, v170
	v_add_u32_e32 v45, 0x1000, v44
	v_mfma_f32_16x16x32_bf16 v[72:75], v[120:123], v[68:71], v[72:75]
	v_add_u32_e32 v32, v32, v172
	v_add_u32_e32 v33, s7, v171
	ds_read2_b64 v[112:115], v45 offset0:32 offset1:36
	ds_read2_b64 v[104:107], v45 offset0:176 offset1:180
	v_add_u32_e32 v44, 0x1800, v44
	s_nop 2
	v_cvt_pk_bf16_f32 v68, v72, v73
	v_cvt_pk_bf16_f32 v69, v74, v75
	v_add_u32_e32 v32, 0x1000, v32
	ds_read_b128 v[100:103], v33 offset:15872
	ds_read_b128 v[96:99], v33 offset:15936
	v_mfma_f32_16x16x32_bf16 v[72:75], v[116:119], v[68:71], v[72:75]
	ds_read2_b64 v[108:111], v44 offset0:64 offset1:68
	ds_read2_b64 v[124:127], v32 offset0:32 offset1:36
	ds_read_b128 v[120:123], v33 offset:16000
	ds_read_b128 v[116:119], v33 offset:16064
	s_lshl_b32 s2, s2, 9
	s_nop 2
	v_cvt_pk_bf16_f32 v68, v72, v73
	v_cvt_pk_bf16_f32 v69, v74, v75
	s_add_i32 s2, s2, 0
	s_add_i32 s2, s2, 0x24800
	s_waitcnt lgkmcnt(9)
; __device__ __forceinline__ void ck_consume(const LAS unsigned char* slot, f32x4 (&sacc)[4], LAS unsigned char* st  , int lane, int cw, f32x4& yout, u32x2& vout, f32x4& dout) {
;     const int n = lane & 15, g = lane >> 4;
;     const f32x4 zero4 = {0.f, 0.f, 0.f, 0.f};
;     u32x2 qlo[2][2], qhi[2][2], mn[4], blo[4], bhi[4]; f32x4 gm[4];
; #pragma unroll
;     for (int ks = 0; ks < 2; ++ks)
; #pragma unroll
;         for (int mt = 0; mt < 2; ++mt) { const LAS unsigned char* p = slot + CK_QR + (16 * mt + n) * 136 + (32 * ks + 4 * g) * 2; qlo[ks][mt] = ck_ld8(p); qhi[ks][mt] = ck_ld8(p + 32); }
;     const u32x2 vq = ck_ld8(slot + CK_VT + (16 * cw + n) * 40 + 8 * g);
;     const u32x2 mk = ck_ld8(slot + CK_MK + n * 40 + 8 * g);
; #pragma unroll
;     for (int j = 0; j < 4; ++j) mn[j] = ck_ld8(slot + CK_MN + j * 640 + n * 40 + 8 * g);
;     const u32x2 ylo = ck_ld8(slot + CK_MY + n * 72 + 8 * g), yhi = ck_ld8(slot + CK_MY + n * 72 + 8 * g + 32);
; #pragma unroll
;     for (int kb = 0; kb < 4; ++kb) { const LAS unsigned char* p = slot + CK_BK + (16 * kb + n) * 72 + 8 * g; blo[kb] = ck_ld8(p); bhi[kb] = ck_ld8(p + 32); gm[kb] = *(const LAS f32x4*)(slot + CK_GM + (16 * kb + 4 * g) * 4); }
;     f32x4 xacc[2] = {zero4, zero4};
; #pragma unroll
;     for (int ks = 0; ks < 2; ++ks) {
;         const pg8::bf16x8 Bs = ck_frag(pkc(sacc[2 * ks][0], sacc[2 * ks][1]), pkc(sacc[2 * ks][2], sacc[2 * ks][3]), pkc(sacc[2 * ks + 1][0], sacc[2 * ks + 1][1]), pkc(sacc[2 * ks + 1][2], sacc[2 * ks + 1][3]));
; #pragma unroll
;         for (int mt = 0; mt < 2; ++mt) xacc[mt] = __builtin_amdgcn_mfma_f32_16x16x32_bf16(ck_frag(qlo[ks][mt].x, qlo[ks][mt].y, qhi[ks][mt].x, qhi[ks][mt].y), Bs, xacc[mt], 0, 0, 0);
;     }
;     f32x4 Z = __builtin_amdgcn_mfma_f32_16x16x32_bf16(ck_frag(0u, 0u, mk.x, mk.y), ck_frag(0u, 0u, vq.x, vq.y), xacc[0], 0, 0, 0);
; #pragma unroll
;     for (int j = 0; j < 4; ++j) Z = __builtin_amdgcn_mfma_f32_16x16x32_bf16(ck_frag(mn[j].x, mn[j].y, 0u, 0u), ck_frag(pkc(Z[0], Z[1]), pkc(Z[2], Z[3]), vq.x, vq.y), Z, 0, 0, 0);
;     const pg8::bf16x8 UV = ck_frag(pkc(Z[0], Z[1]), pkc(Z[2], Z[3]), vq.x, vq.y);
;     { const f32x4 y = __builtin_amdgcn_mfma_f32_16x16x32_bf16(ck_frag(ylo.x, ylo.y, yhi.x, yhi.y), UV, xacc[1], 0, 0, 0);
;       yout = y; vout = vq; dout = *(const LAS f32x4*)(slot + CK_DOT + 16 * g);
; #pragma unroll
	v_mfma_f32_16x16x32_bf16 v[72:75], v[242:245], v[68:71], v[72:75]
	v_add_u32_e32 v139, s2, v173
	s_nop 6
	v_cvt_pk_bf16_f32 v68, v72, v73
	v_cvt_pk_bf16_f32 v69, v74, v75
	ds_read_b128 v[72:75], v33 offset:16128
	s_waitcnt lgkmcnt(9)
	v_mfma_f32_16x16x32_bf16 v[76:79], v[246:249], v[68:71], v[76:79]
	s_waitcnt lgkmcnt(3)
	v_mfma_f32_16x16x32_bf16 v[88:91], v[104:107], v[68:71], v[88:91]
	s_waitcnt lgkmcnt(0)
	v_mfma_f32_16x16x32_bf16 v[84:87], v[108:111], v[68:71], v[84:87]
	v_mfma_f32_16x16x32_bf16 v[92:95], v[112:115], v[68:71], v[92:95]
	s_waitcnt lgkmcnt(0)
	v_mfma_f32_16x16x32_bf16 v[80:83], v[124:127], v[68:71], v[80:83]
	s_nop 0
	v_mul_f32_e32 v45, v76, v76
	v_mov_b32_dpp v32, v76 quad_perm:[1,0,3,2] row_mask:0xf bank_mask:0xf bound_ctrl:1
	v_mov_b32_e32 v44, v76
	v_mov_b32_dpp v33, v45 quad_perm:[1,0,3,2] row_mask:0xf bank_mask:0xf bound_ctrl:1
	v_pk_add_f32 v[32:33], v[44:45], v[32:33]
	s_nop 1
	v_mov_b32_dpp v44, v32 quad_perm:[2,3,0,1] row_mask:0xf bank_mask:0xf bound_ctrl:1
	v_mov_b32_dpp v45, v33 quad_perm:[2,3,0,1] row_mask:0xf bank_mask:0xf bound_ctrl:1
	v_pk_add_f32 v[32:33], v[32:33], v[44:45]
	s_nop 1
	v_mov_b32_dpp v44, v32 row_half_mirror row_mask:0xf bank_mask:0xf bound_ctrl:1
	v_mov_b32_dpp v45, v33 row_half_mirror row_mask:0xf bank_mask:0xf bound_ctrl:1
	v_pk_add_f32 v[32:33], v[32:33], v[44:45]
	s_nop 1
	v_mov_b32_dpp v44, v32 row_mirror row_mask:0xf bank_mask:0xf bound_ctrl:1
	v_mov_b32_dpp v45, v33 row_mirror row_mask:0xf bank_mask:0xf bound_ctrl:1
	s_and_saveexec_b64 s[34:35], s[40:41]
	v_pk_add_f32 v[32:33], v[32:33], v[44:45]
	ds_write_b64 v139, v[32:33]
	s_or_b64 exec, exec, s[34:35]
	v_mul_f32_e32 v45, v77, v77
	v_mov_b32_dpp v32, v77 quad_perm:[1,0,3,2] row_mask:0xf bank_mask:0xf bound_ctrl:1
	v_mov_b32_e32 v44, v77
	v_mov_b32_dpp v33, v45 quad_perm:[1,0,3,2] row_mask:0xf bank_mask:0xf bound_ctrl:1
	v_pk_add_f32 v[32:33], v[44:45], v[32:33]
	s_nop 1
	v_mov_b32_dpp v44, v32 quad_perm:[2,3,0,1] row_mask:0xf bank_mask:0xf bound_ctrl:1
	v_mov_b32_dpp v45, v33 quad_perm:[2,3,0,1] row_mask:0xf bank_mask:0xf bound_ctrl:1
	v_pk_add_f32 v[32:33], v[32:33], v[44:45]
	s_nop 1
	v_mov_b32_dpp v44, v32 row_half_mirror row_mask:0xf bank_mask:0xf bound_ctrl:1
	v_mov_b32_dpp v45, v33 row_half_mirror row_mask:0xf bank_mask:0xf bound_ctrl:1
	v_pk_add_f32 v[32:33], v[32:33], v[44:45]
	s_nop 1
	v_mov_b32_dpp v44, v32 row_mirror row_mask:0xf bank_mask:0xf bound_ctrl:1
	v_mov_b32_dpp v45, v33 row_mirror row_mask:0xf bank_mask:0xf bound_ctrl:1
	s_and_saveexec_b64 s[34:35], s[40:41]
	v_pk_add_f32 v[32:33], v[32:33], v[44:45]
	ds_write_b64 v139, v[32:33] offset:32
	s_or_b64 exec, exec, s[34:35]
	v_mul_f32_e32 v45, v78, v78
	v_mov_b32_dpp v32, v78 quad_perm:[1,0,3,2] row_mask:0xf bank_mask:0xf bound_ctrl:1
	v_mov_b32_e32 v44, v78
	v_mov_b32_dpp v33, v45 quad_perm:[1,0,3,2] row_mask:0xf bank_mask:0xf bound_ctrl:1
	v_pk_add_f32 v[32:33], v[44:45], v[32:33]
	s_nop 1
	v_mov_b32_dpp v44, v32 quad_perm:[2,3,0,1] row_mask:0xf bank_mask:0xf bound_ctrl:1
	v_mov_b32_dpp v45, v33 quad_perm:[2,3,0,1] row_mask:0xf bank_mask:0xf bound_ctrl:1
	v_pk_add_f32 v[32:33], v[32:33], v[44:45]
	s_nop 1
	v_mov_b32_dpp v44, v32 row_half_mirror row_mask:0xf bank_mask:0xf bound_ctrl:1
	v_mov_b32_dpp v45, v33 row_half_mirror row_mask:0xf bank_mask:0xf bound_ctrl:1
	v_pk_add_f32 v[32:33], v[32:33], v[44:45]
	s_nop 1
	v_mov_b32_dpp v44, v32 row_mirror row_mask:0xf bank_mask:0xf bound_ctrl:1
	v_mov_b32_dpp v45, v33 row_mirror row_mask:0xf bank_mask:0xf bound_ctrl:1
	s_and_saveexec_b64 s[34:35], s[40:41]
	v_pk_add_f32 v[32:33], v[32:33], v[44:45]
	ds_write_b64 v139, v[32:33] offset:64
	s_or_b64 exec, exec, s[34:35]
	v_mul_f32_e32 v45, v79, v79
	v_mov_b32_dpp v32, v79 quad_perm:[1,0,3,2] row_mask:0xf bank_mask:0xf bound_ctrl:1
	v_mov_b32_e32 v44, v79
	v_mov_b32_dpp v33, v45 quad_perm:[1,0,3,2] row_mask:0xf bank_mask:0xf bound_ctrl:1
	v_pk_add_f32 v[32:33], v[44:45], v[32:33]
	s_nop 1
	v_mov_b32_dpp v44, v32 quad_perm:[2,3,0,1] row_mask:0xf bank_mask:0xf bound_ctrl:1
	v_mov_b32_dpp v45, v33 quad_perm:[2,3,0,1] row_mask:0xf bank_mask:0xf bound_ctrl:1
	v_pk_add_f32 v[32:33], v[32:33], v[44:45]
	s_nop 1
	v_mov_b32_dpp v44, v32 row_half_mirror row_mask:0xf bank_mask:0xf bound_ctrl:1
	v_mov_b32_dpp v45, v33 row_half_mirror row_mask:0xf bank_mask:0xf bound_ctrl:1
	v_pk_add_f32 v[32:33], v[32:33], v[44:45]
	s_nop 1
	v_mov_b32_dpp v44, v32 row_mirror row_mask:0xf bank_mask:0xf bound_ctrl:1
	v_mov_b32_dpp v45, v33 row_mirror row_mask:0xf bank_mask:0xf bound_ctrl:1
	s_and_saveexec_b64 s[34:35], s[40:41]
	v_pk_add_f32 v[32:33], v[32:33], v[44:45]
	ds_write_b64 v139, v[32:33] offset:96
	s_or_b64 exec, exec, s[34:35]
	v_add_co_u32_e32 v32, vcc, 0x30000, v158
	v_addc_co_u32_e32 v33, vcc, 0, v159, vcc
	v_add_co_u32_e32 v104, vcc, 0x31000, v158
	v_addc_co_u32_e32 v105, vcc, 0, v159, vcc
	v_add_co_u32_e32 v106, vcc, 0x32000, v158
	s_nop 0
	v_addc_co_u32_e32 v107, vcc, 0, v159, vcc
	v_add_co_u32_e32 v108, vcc, 0x33000, v158
	v_addc_co_u32_e32 v109, vcc, 0, v159, vcc
	global_load_ushort v44, v[32:33], off
	global_load_ushort v45, v[104:105], off
	s_nop 0
	global_load_ushort v104, v[106:107], off
	global_load_ushort v105, v[108:109], off
	v_pk_mul_f32 v[94:95], v[102:103], v[94:95]
	v_pk_mul_f32 v[92:93], v[100:101], v[92:93]
	v_pk_mul_f32 v[90:91], v[98:99], v[90:91]
	v_pk_mul_f32 v[88:89], v[96:97], v[88:89]
	s_waitcnt lgkmcnt(2)
	v_pk_mul_f32 v[86:87], v[122:123], v[86:87]
	v_pk_mul_f32 v[84:85], v[120:121], v[84:85]
	s_waitcnt lgkmcnt(1)
	v_pk_mul_f32 v[82:83], v[118:119], v[82:83]
	v_pk_mul_f32 v[80:81], v[116:117], v[80:81]
	s_waitcnt lgkmcnt(0)
	s_barrier
	s_add_i32 s10, s10, 64
	s_addk_i32 s27, 0x800
	s_add_i32 s28, s28, -1
	v_add_u32_e32 v128, 0x20000, v128
	s_add_i32 s29, s29, 4
	s_branch .LBB0_116
